# adds: prep tile issues the PART row loads for dt before the first tile barrier (waves 0-1) so their latency overlaps the LDS staging
# speedup vs baseline: 1.0267x; 1.0076x over previous
.LBB0_539:
	s_or_b64 exec, exec, s[14:15]
	s_waitcnt vmcnt(7)
	v_mfma_f32_16x16x32_bf16 v[46:49], v[58:61], v[46:49], 0
	s_waitcnt vmcnt(6)
	v_mfma_f32_16x16x32_bf16 v[46:49], v[62:65], v[50:53], v[46:49]
	s_waitcnt vmcnt(3)
	v_mfma_f32_16x16x32_bf16 v[46:49], v[74:77], v[66:69], v[46:49]
	s_waitcnt vmcnt(2)
	v_mfma_f32_16x16x32_bf16 v[46:49], v[78:81], v[70:73], v[46:49]
	v_readlane_b32 s98, v253, 50
	v_readlane_b32 s99, v253, 51
	v_add_u32_e32 v220, s33, v129
	v_ashrrev_i32_e32 v221, 31, v220
	v_lshlrev_b64 v[220:221], 6, v[220:221]
	s_and_saveexec_b64 s[100:101], s[6:7]
	s_cbranch_execz .Lprep_part_skip
	v_lshl_add_u64 v[220:221], s[98:99], 0, v[220:221]
	global_load_dwordx4 v[222:225], v[220:221], off offset:32
	global_load_dwordx4 v[226:229], v[220:221], off offset:16
	global_load_dwordx4 v[230:233], v[220:221], off
	global_load_dwordx4 v[234:237], v[220:221], off offset:48
.Lprep_part_skip:
	s_or_b64 exec, exec, s[100:101]
	s_and_saveexec_b64 s[14:15], s[4:5]
	s_cbranch_execnz .LBB0_566
	s_or_b64 exec, exec, s[14:15]
	s_and_saveexec_b64 s[14:15], s[10:11]
	s_cbranch_execnz .LBB0_567

.LBB0_543:
	s_or_b64 exec, exec, s[14:15]
	v_add_u32_e32 v50, s44, v89
	ds_read_b32 v0, v128
	v_cvt_f32_i32_e32 v42, v50
	s_waitcnt lgkmcnt(0)
	v_mul_f32_e32 v0, v0, v42
	v_mul_f32_e32 v42, 0.15915494, v0
	v_rndne_f32_e32 v42, v42
	v_fmac_f32_e32 v0, 0xc0c90fdb, v42
	v_fmac_f32_e32 v0, 0x343bbd2e, v42
	v_mul_f32_e32 v0, 0.15915494, v0
	v_sin_f32_e32 v43, v0
	v_cos_f32_e32 v42, v0
	v_add_u32_e32 v0, 0, v87
	v_add_u32_e32 v0, 0x1bc00, v0
	ds_write_b64 v0, v[42:43]
	s_waitcnt lgkmcnt(0)
	s_barrier
	s_and_saveexec_b64 s[14:15], s[6:7]
	s_cbranch_execz .LBB0_547
	ds_read2st64_b32 v[42:43], v130 offset1:2
	v_readlane_b32 s28, v253, 50
	v_readlane_b32 s29, v253, 51
	s_waitcnt lgkmcnt(0)
	v_add_f32_e32 v0, 0, v42
	v_add_f32_e32 v0, v0, v43
	ds_read2st64_b32 v[42:43], v130 offset0:4 offset1:6
	s_waitcnt lgkmcnt(0)
	v_add_f32_e32 v0, v0, v42
	v_add_f32_e32 v0, v0, v43
	ds_read2st64_b32 v[42:43], v130 offset0:8 offset1:10
	s_waitcnt lgkmcnt(0)
	v_add_f32_e32 v0, v0, v42
	v_add_f32_e32 v0, v0, v43
	ds_read2st64_b32 v[42:43], v130 offset0:12 offset1:14
	s_waitcnt lgkmcnt(0)
	v_add_f32_e32 v0, v0, v42
	v_add_u32_e32 v42, s33, v129
	v_add_f32_e32 v51, v0, v43
	v_ashrrev_i32_e32 v43, 31, v42
	v_lshlrev_b64 v[44:45], 6, v[42:43]
	s_waitcnt vmcnt(0)
	v_mov_b64_e32 v[44:45], v[222:223]
	v_mov_b64_e32 v[46:47], v[224:225]
	v_mov_b64_e32 v[52:53], v[226:227]
	v_mov_b64_e32 v[54:55], v[228:229]
	v_mov_b64_e32 v[56:57], v[230:231]
	v_mov_b64_e32 v[58:59], v[232:233]
	v_mov_b64_e32 v[60:61], v[234:235]
	v_mov_b64_e32 v[62:63], v[236:237]
	s_mov_b32 s28, 0x800000
	v_mov_b32_e32 v0, v45
	v_mov_b32_e32 v64, v53
	v_mov_b32_e32 v48, v57
	v_mov_b32_e32 v49, v58
	v_mov_b32_e32 v65, v54
	v_mov_b32_e32 v57, v59
	v_mov_b32_e32 v53, v55
	v_pk_add_f32 v[48:49], v[48:49], v[56:57]
	v_pk_add_f32 v[52:53], v[64:65], v[52:53]
	v_pk_add_f32 v[44:45], v[44:45], v[0:1]
	v_mov_b32_e32 v0, v47
	v_pk_add_f32 v[48:49], v[48:49], v[48:49] op_sel:[0,1] op_sel_hi:[1,0]
	v_pk_add_f32 v[52:53], v[52:53], v[52:53] op_sel:[0,1] op_sel_hi:[1,0]
	v_pk_add_f32 v[46:47], v[46:47], v[0:1]
	v_mov_b32_e32 v49, v60
	v_mov_b32_e32 v53, v61
	v_mov_b32_e32 v45, v62
	v_mov_b32_e32 v47, v63
	v_pk_add_f32 v[48:49], v[48:49], v[52:53]
	v_pk_add_f32 v[44:45], v[44:45], v[46:47]
	s_nop 0
	v_pk_add_f32 v[44:45], v[48:49], v[44:45]
	s_nop 0
	v_add_f32_e32 v0, v44, v45
	v_fmamk_f32 v0, v0, 0x3a800000, v241
	v_cmp_gt_f32_e32 vcc, s28, v0
	v_mul_f32_e32 v44, 0x4b800000, v0
	v_readlane_b32 s28, v253, 42
	v_cndmask_b32_e32 v0, v0, v44, vcc
	v_readlane_b32 s29, v253, 43
	v_rsq_f32_e32 v0, v0
	s_nop 0
	v_mul_f32_e32 v44, 0x45800000, v0
	v_cndmask_b32_e32 v46, v0, v44, vcc
	v_mov_b32_e32 v0, v192
	s_mov_b32 s28, 0x41a00000
	v_fmac_f32_e32 v0, v51, v46
	v_cmp_nlt_f32_e32 vcc, s28, v0
	s_and_saveexec_b64 s[28:29], vcc
	s_cbranch_execz .LBB0_546
	v_mul_f32_e32 v0, 0x3fb8aa3b, v0
	v_exp_f32_e32 v0, v0
	s_mov_b32 s30, 0x3f2aaaab
	v_add_f32_e32 v46, 1.0, v0
	v_frexp_mant_f32_e32 v48, v46
	v_cvt_f64_f32_e32 v[44:45], v46
	v_frexp_exp_i32_f64_e32 v44, v[44:45]
	v_cmp_gt_f32_e32 vcc, s30, v48
	v_add_f32_e32 v47, -1.0, v46
	v_sub_f32_e32 v49, v47, v46
	v_subbrev_co_u32_e32 v51, vcc, 0, v44, vcc
	v_sub_u32_e32 v44, 0, v51
	v_sub_f32_e32 v47, v0, v47
	v_add_f32_e32 v49, 1.0, v49
	v_ldexp_f32 v45, v46, v44
	v_add_f32_e32 v47, v47, v49
	v_add_f32_e32 v46, -1.0, v45
	v_add_f32_e32 v48, 1.0, v45
	v_ldexp_f32 v44, v47, v44
	v_add_f32_e32 v47, 1.0, v46
	v_add_f32_e32 v49, -1.0, v48
	v_sub_f32_e32 v47, v45, v47
	v_sub_f32_e32 v45, v45, v49
	v_add_f32_e32 v47, v44, v47
	v_add_f32_e32 v44, v44, v45
	v_add_f32_e32 v54, v48, v44
	v_rcp_f32_e32 v56, v54
	v_sub_f32_e32 v45, v54, v48
	v_sub_f32_e32 v55, v44, v45
	v_add_f32_e32 v45, v46, v47
	v_mul_f32_e32 v58, v45, v56
	v_sub_f32_e32 v44, v45, v46
	v_mul_f32_e32 v46, v54, v58
	v_fma_f32 v48, v58, v54, -v46
	v_fmac_f32_e32 v48, v58, v55
	v_sub_f32_e32 v57, v47, v44
	v_add_f32_e32 v44, v46, v48
	v_sub_f32_e32 v47, v45, v44
	v_pk_add_f32 v[52:53], v[44:45], v[46:47] neg_lo:[0,1] neg_hi:[0,1]
	v_mov_b32_e32 v49, v44
	v_pk_add_f32 v[44:45], v[52:53], v[48:49] neg_lo:[0,1] neg_hi:[0,1]
	s_mov_b32 s30, 0x3f317218
	v_add_f32_e32 v45, v57, v45
	v_add_f32_e32 v44, v44, v45
	v_add_f32_e32 v45, v47, v44
	v_mul_f32_e32 v57, v56, v45
	v_mul_f32_e32 v46, v54, v57
	v_fma_f32 v48, v57, v54, -v46
	v_fmac_f32_e32 v48, v57, v55
	v_sub_f32_e32 v47, v47, v45
	v_add_f32_e32 v54, v44, v47
	v_add_f32_e32 v44, v46, v48
	v_sub_f32_e32 v47, v45, v44
	v_pk_add_f32 v[52:53], v[44:45], v[46:47] neg_lo:[0,1] neg_hi:[0,1]
	v_mov_b32_e32 v49, v44
	v_pk_add_f32 v[44:45], v[52:53], v[48:49] neg_lo:[0,1] neg_hi:[0,1]
	s_nop 0
	v_add_f32_e32 v45, v54, v45
	v_add_f32_e32 v44, v44, v45
	v_add_f32_e32 v45, v58, v57
	v_add_f32_e32 v44, v47, v44
	v_sub_f32_e32 v46, v45, v58
	v_mul_f32_e32 v44, v56, v44
	v_sub_f32_e32 v46, v57, v46
	v_add_f32_e32 v46, v46, v44
	v_add_f32_e32 v48, v45, v46
	v_mul_f32_e32 v49, v48, v48
	v_mov_b32_e32 v44, 0x3ecc95a3
	v_fmamk_f32 v44, v49, 0x3e9b6dac, v44
	v_fmaak_f32 v195, v49, v44, 0x3f2aaada
	v_cvt_f32_i32_e32 v44, v51
	v_sub_f32_e32 v45, v48, v45
	v_sub_f32_e32 v45, v46, v45
	v_ldexp_f32 v51, v45, 1
	v_mul_f32_e32 v45, v48, v49
	v_ldexp_f32 v47, v48, 1
	v_pk_mul_f32 v[48:49], v[44:45], v[194:195]
	s_nop 0
	v_fma_f32 v46, v44, s30, -v48
	v_fmac_f32_e32 v46, 0xb102e308, v44
	v_pk_add_f32 v[44:45], v[48:49], v[46:47]
	v_mov_b32_e32 v52, v48
	v_sub_f32_e32 v47, v45, v47
	v_sub_f32_e32 v47, v49, v47
	v_add_f32_e32 v53, v51, v47
	v_pk_add_f32 v[48:49], v[44:45], v[48:49] neg_lo:[0,1] neg_hi:[0,1]
	v_pk_add_f32 v[54:55], v[44:45], v[52:53]
	v_mov_b32_e32 v47, v44
	v_mov_b32_e32 v49, v55
	v_pk_add_f32 v[56:57], v[46:47], v[48:49] neg_lo:[0,1] neg_hi:[0,1]
	v_pk_add_f32 v[46:47], v[46:47], v[48:49]
	v_mov_b32_e32 v52, v53
	v_pk_add_f32 v[48:49], v[46:47], v[44:45] op_sel:[1,0] op_sel_hi:[0,1] neg_lo:[0,1] neg_hi:[0,1]
	v_pk_add_f32 v[58:59], v[54:55], v[48:49] op_sel_hi:[1,0] neg_lo:[0,1] neg_hi:[0,1]
	v_mov_b32_e32 v54, v55
	v_mov_b32_e32 v55, v47
	v_pk_mov_b32 v[48:49], v[44:45], v[48:49] op_sel:[1,0]
	v_mov_b32_e32 v53, v44
	v_pk_add_f32 v[48:49], v[54:55], v[48:49] neg_lo:[0,1] neg_hi:[0,1]
	v_mov_b32_e32 v58, v56
	v_pk_add_f32 v[44:45], v[52:53], v[48:49] neg_lo:[0,1] neg_hi:[0,1]
	v_mov_b32_e32 v57, v47
	v_pk_add_f32 v[48:49], v[58:59], v[44:45]
	s_mov_b32 s30, 0x7f800000
	v_pk_add_f32 v[52:53], v[48:49], v[48:49] op_sel:[0,1] op_sel_hi:[1,0]
	v_cmp_neq_f32_e32 vcc, s30, v0
	v_pk_add_f32 v[46:47], v[46:47], v[52:53] op_sel:[1,0] op_sel_hi:[0,1]
	v_mov_b32_e32 v49, v46
	v_pk_add_f32 v[54:55], v[48:49], v[56:57] neg_lo:[0,1] neg_hi:[0,1]
	v_mov_b32_e32 v45, v52
	v_sub_f32_e32 v47, v48, v54
	v_pk_add_f32 v[44:45], v[44:45], v[54:55] neg_lo:[0,1] neg_hi:[0,1]
	v_sub_f32_e32 v47, v56, v47
	v_add_f32_e32 v44, v44, v47
	v_add_f32_e32 v44, v44, v45
	v_add_f32_e32 v44, v46, v44
	v_mov_b32_e32 v45, 0x7f800000
	v_cndmask_b32_e32 v44, v45, v44, vcc
	v_cmp_ngt_f32_e32 vcc, -1.0, v0
	s_mov_b32 s30, 0x33800000
	s_nop 0
	v_cndmask_b32_e32 v44, v248, v44, vcc
	v_cmp_neq_f32_e32 vcc, -1.0, v0
	s_nop 1
	v_cndmask_b32_e32 v44, v244, v44, vcc
	v_cmp_lt_f32_e64 vcc, |v0|, s30
	s_nop 1
	v_cndmask_b32_e32 v0, v44, v0, vcc
